# prompt attention block A: score accumulators start at minus the running max (C operand), removing 32 subtracts per tile-step
# speedup vs baseline: 1.0241x; 1.0015x over previous
.LBB0_977:
	v_mov_b32_e32 v34, v179
	v_mov_b32_e32 v35, v179
	v_mov_b32_e32 v48, v179
	v_mov_b32_e32 v49, v179
	s_xor_b64 s[38:39], s[6:7], -1
	s_lshl_b32 s6, s13, 2
	v_add_u32_e32 v202, v2, v188
	v_mov_b32_e32 v36, v179
	v_mov_b32_e32 v37, v179
	v_mov_b32_e32 v38, v179
	v_mov_b32_e32 v39, v179
	v_mov_b32_e32 v40, v179
	v_mov_b32_e32 v41, v179
	v_mov_b32_e32 v42, v179
	v_mov_b32_e32 v43, v179
	v_mov_b32_e32 v44, v179
	v_mov_b32_e32 v45, v179
	v_mov_b32_e32 v46, v179
	v_mov_b32_e32 v47, v179
	v_mov_b64_e32 v[64:65], v[48:49]
	v_mov_b64_e32 v[2:3], v[34:35]
	v_mov_b64_e32 v[18:19], v[34:35]
	s_add_i32 s82, s6, 4
	s_or_b32 s83, s12, s6
	s_or_b32 s75, s6, 3
	s_or_b32 s84, s1, 32
	s_mov_b32 s6, 0
	v_mov_b32_e32 v201, 0
	s_mov_b32 s85, 0xa000
	s_movk_i32 s86, 0x5000
	v_mov_b64_e32 v[62:63], v[46:47]
	v_mov_b64_e32 v[60:61], v[44:45]
	v_mov_b64_e32 v[58:59], v[42:43]
	v_mov_b64_e32 v[56:57], v[40:41]
	v_mov_b64_e32 v[54:55], v[38:39]
	v_mov_b64_e32 v[52:53], v[36:37]
	v_mov_b64_e32 v[50:51], v[34:35]
	v_mov_b64_e32 v[4:5], v[36:37]
	v_mov_b64_e32 v[6:7], v[38:39]
	v_mov_b64_e32 v[8:9], v[40:41]
	v_mov_b64_e32 v[10:11], v[42:43]
	v_mov_b64_e32 v[12:13], v[44:45]
	v_mov_b64_e32 v[14:15], v[46:47]
	v_mov_b64_e32 v[16:17], v[48:49]
	v_mov_b64_e32 v[20:21], v[36:37]
	v_mov_b64_e32 v[22:23], v[38:39]
	v_mov_b64_e32 v[24:25], v[40:41]
	v_mov_b64_e32 v[26:27], v[42:43]
	v_mov_b64_e32 v[28:29], v[44:45]
	v_mov_b64_e32 v[30:31], v[46:47]
	v_mov_b64_e32 v[32:33], v[48:49]
	s_mov_b32 s87, 0
	v_mov_b32_e32 v204, 0
	v_mov_b32_e32 v203, 0
	v_mov_b32_e32 v205, 0
	v_mov_b32_e32 v230, 0
	v_mov_b32_e32 v231, 0
	v_mov_b32_e32 v232, 0
	v_mov_b32_e32 v233, 0
	v_mov_b32_e32 v234, 0
	v_mov_b32_e32 v235, 0
	v_mov_b32_e32 v236, 0
	v_mov_b32_e32 v237, 0
	v_mov_b32_e32 v238, 0
	v_mov_b32_e32 v239, 0
	v_mov_b32_e32 v240, 0
	v_mov_b32_e32 v241, 0
	v_mov_b32_e32 v242, 0
	v_mov_b32_e32 v243, 0
	v_mov_b32_e32 v244, 0
	v_mov_b32_e32 v245, 0
.LBB0_978:
	s_add_i32 s89, s87, 2
	s_mov_b32 s88, s6
	s_cmp_gt_u32 s87, s83
	s_cbranch_scc1 .LBB0_984
	v_mov_b32_e32 v66, v189
	v_mov_b32_e32 v206, v192
	s_add_i32 s90, s88, 0
	s_cmp_eq_u32 s87, s83
	v_lshlrev_b32_e32 v80, 5, v66
	v_add_u32_e32 v66, s90, v190
	v_add_u32_e32 v66, v66, v80
	ds_read_b128 v[68:71], v66
	ds_read_b128 v[72:75], v66 offset:8192
	v_xad_u32 v67, v80, 32, s90
	v_add_u32_e32 v67, v67, v190
	ds_read_b128 v[76:79], v67
	ds_read_b128 v[98:101], v67 offset:8192
	s_waitcnt lgkmcnt(3)
	v_mfma_f32_32x32x16_bf16 v[114:129], v[68:71], v[138:141], v[230:245]
	s_cselect_b64 s[70:71], -1, 0
	s_lshl_b32 s6, s87, 6
	s_sub_i32 s91, 0, s6
	s_cmp_lg_u32 s87, s83
	s_waitcnt lgkmcnt(2)
	v_mfma_f32_32x32x16_bf16 v[82:97], v[72:75], v[138:141], v[230:245]
	s_waitcnt lgkmcnt(1)
	v_mfma_f32_32x32x16_bf16 v[114:129], v[76:79], v[142:145], v[114:129]
	v_xad_u32 v68, v80, 64, s90
	v_add_u32_e32 v210, v68, v190
	ds_read_b128 v[68:71], v210
	ds_read_b128 v[72:75], v210 offset:8192
	s_waitcnt lgkmcnt(2)
	v_mfma_f32_32x32x16_bf16 v[82:97], v[98:101], v[142:145], v[82:97]
	v_xor_b32_e32 v76, 0x60, v80
	s_waitcnt lgkmcnt(1)
	v_mfma_f32_32x32x16_bf16 v[114:129], v[68:71], v[154:157], v[114:129]
	v_add_u32_e32 v76, s90, v76
	v_add_u32_e32 v209, v76, v190
	ds_read_b128 v[76:79], v209
	ds_read_b128 v[98:101], v209 offset:8192
	s_waitcnt lgkmcnt(2)
	v_mfma_f32_32x32x16_bf16 v[82:97], v[72:75], v[154:157], v[82:97]
	s_waitcnt lgkmcnt(1)
	v_mfma_f32_32x32x16_bf16 v[114:129], v[76:79], v[158:161], v[114:129]
	v_add_u32_e32 v68, s90, v193
	v_add_u32_e32 v208, v68, v191
	ds_read_b128 v[68:71], v208 offset:16384
	ds_read_b128 v[72:75], v208 offset:18432
	s_waitcnt lgkmcnt(2)
	v_mfma_f32_32x32x16_bf16 v[82:97], v[98:101], v[158:161], v[82:97]
	s_waitcnt lgkmcnt(1)
	v_mfma_f32_32x32x16_bf16 v[114:129], v[68:71], v[170:173], v[114:129]
	v_add_u32_e32 v76, s90, v194
	v_add_u32_e32 v207, v76, v191
	ds_read_b128 v[76:79], v207 offset:16384
	ds_read_b128 v[98:101], v207 offset:18432
	s_waitcnt lgkmcnt(2)
	v_mfma_f32_32x32x16_bf16 v[82:97], v[72:75], v[170:173], v[82:97]
	s_waitcnt lgkmcnt(1)
	v_mfma_f32_32x32x16_bf16 v[114:129], v[76:79], v[174:177], v[114:129]
	s_waitcnt lgkmcnt(0)
	v_mfma_f32_32x32x16_bf16 v[82:97], v[98:101], v[174:177], v[82:97]
	s_cbranch_scc1 .LBB0_981
	v_mov_b32_e32 v68, v1
	s_add_i32 s6, s91, s1
	v_ashrrev_i32_e32 v69, 3, v68
	v_and_b32_e32 v69, -4, v69
	v_and_or_b32 v68, v68, 31, s6
	v_sub_u32_e32 v68, v68, v69
	s_nop 0
	v_cmp_gt_i32_e64 s[66:67], 26, v68
	v_cmp_gt_i32_e64 s[68:69], 27, v68
	v_cmp_gt_i32_e64 s[64:65], 25, v68
	s_and_b64 s[66:67], s[68:69], s[66:67]
	v_cmp_gt_i32_e64 s[62:63], 24, v68
	s_and_b64 s[64:65], s[66:67], s[64:65]
	v_cmp_gt_i32_e64 s[60:61], 19, v68
	s_and_b64 s[62:63], s[64:65], s[62:63]
	v_cmp_gt_i32_e64 s[58:59], 18, v68
	s_and_b64 s[60:61], s[62:63], s[60:61]
	v_cmp_gt_i32_e64 s[56:57], 17, v68
	s_and_b64 s[58:59], s[60:61], s[58:59]
	v_cmp_gt_i32_e64 s[54:55], 16, v68
	s_and_b64 s[56:57], s[58:59], s[56:57]
	v_cmp_gt_i32_e64 s[52:53], 11, v68
	s_and_b64 s[54:55], s[56:57], s[54:55]
	v_cmp_gt_i32_e64 s[50:51], 10, v68
	s_and_b64 s[52:53], s[54:55], s[52:53]
	v_cmp_gt_i32_e64 s[48:49], 9, v68
	s_and_b64 s[50:51], s[52:53], s[50:51]
	v_cmp_gt_i32_e64 s[46:47], 8, v68
	s_and_b64 s[48:49], s[50:51], s[48:49]
	v_cmp_gt_i32_e64 s[44:45], 3, v68
	s_and_b64 s[46:47], s[48:49], s[46:47]
	v_cmp_gt_i32_e64 s[42:43], 2, v68
	s_and_b64 s[44:45], s[46:47], s[44:45]
	v_cmp_gt_i32_e64 s[40:41], 1, v68
	s_and_b64 s[42:43], s[44:45], s[42:43]
	v_cmp_gt_i32_e64 s[36:37], 0, v68
	s_and_b64 s[40:41], s[42:43], s[40:41]
	s_and_b64 s[36:37], s[40:41], s[36:37]
	v_cmp_gt_i32_e64 s[34:35], 58, v68
	v_cndmask_b32_e64 v114, v114, v200, s[36:37]
	v_cmp_gt_i32_e64 s[36:37], 59, v68
	v_cmp_gt_i32_e64 s[30:31], 57, v68
	s_and_b64 s[34:35], s[36:37], s[34:35]
	v_cmp_gt_i32_e64 s[28:29], 56, v68
	s_and_b64 s[30:31], s[34:35], s[30:31]
	v_cmp_gt_i32_e64 s[26:27], 51, v68
	s_and_b64 s[28:29], s[30:31], s[28:29]
	v_cmp_gt_i32_e64 s[24:25], 50, v68
	s_and_b64 s[26:27], s[28:29], s[26:27]
	v_cmp_gt_i32_e64 s[22:23], 49, v68
	s_and_b64 s[24:25], s[26:27], s[24:25]
	v_cmp_gt_i32_e64 s[20:21], 48, v68
	s_and_b64 s[22:23], s[24:25], s[22:23]
	v_cmp_gt_i32_e64 s[18:19], 43, v68
	s_and_b64 s[20:21], s[22:23], s[20:21]
	v_cmp_gt_i32_e64 s[16:17], 42, v68
	s_and_b64 s[18:19], s[20:21], s[18:19]
	v_cmp_gt_i32_e64 s[14:15], 41, v68
	s_and_b64 s[16:17], s[18:19], s[16:17]
	v_cmp_gt_i32_e64 s[12:13], 40, v68
	s_and_b64 s[14:15], s[16:17], s[14:15]
	v_cmp_gt_i32_e64 s[10:11], 35, v68
	s_and_b64 s[12:13], s[14:15], s[12:13]
	v_cmp_gt_i32_e64 s[8:9], 34, v68
	s_and_b64 s[10:11], s[12:13], s[10:11]
	v_cmp_gt_i32_e64 s[6:7], 33, v68
	s_and_b64 s[8:9], s[10:11], s[8:9]
	v_cmp_gt_i32_e32 vcc, 32, v68
	s_and_b64 s[6:7], s[8:9], s[6:7]
	s_and_b64 vcc, s[6:7], vcc
	v_cndmask_b32_e64 v129, v129, v200, s[68:69]
	v_cndmask_b32_e64 v128, v128, v200, s[66:67]
	v_cndmask_b32_e64 v127, v127, v200, s[64:65]
	v_cndmask_b32_e64 v126, v126, v200, s[62:63]
	v_cndmask_b32_e64 v125, v125, v200, s[60:61]
	v_cndmask_b32_e64 v124, v124, v200, s[58:59]
	v_cndmask_b32_e64 v123, v123, v200, s[56:57]
	v_cndmask_b32_e64 v122, v122, v200, s[54:55]
	v_cndmask_b32_e64 v121, v121, v200, s[52:53]
	v_cndmask_b32_e64 v120, v120, v200, s[50:51]
	v_cndmask_b32_e64 v119, v119, v200, s[48:49]
	v_cndmask_b32_e64 v118, v118, v200, s[46:47]
	v_cndmask_b32_e64 v117, v117, v200, s[44:45]
	v_cndmask_b32_e64 v116, v116, v200, s[42:43]
	v_cndmask_b32_e64 v115, v115, v200, s[40:41]
	v_cndmask_b32_e64 v97, v97, v200, s[36:37]
	v_cndmask_b32_e64 v96, v96, v200, s[34:35]
	v_cndmask_b32_e64 v95, v95, v200, s[30:31]
	v_cndmask_b32_e64 v94, v94, v200, s[28:29]
	v_cndmask_b32_e64 v93, v93, v200, s[26:27]
	v_cndmask_b32_e64 v92, v92, v200, s[24:25]
	v_cndmask_b32_e64 v91, v91, v200, s[22:23]
	v_cndmask_b32_e64 v90, v90, v200, s[20:21]
	v_cndmask_b32_e64 v89, v89, v200, s[18:19]
	v_cndmask_b32_e64 v88, v88, v200, s[16:17]
	v_cndmask_b32_e64 v87, v87, v200, s[14:15]
	v_cndmask_b32_e64 v86, v86, v200, s[12:13]
	v_cndmask_b32_e64 v85, v85, v200, s[10:11]
	v_cndmask_b32_e64 v84, v84, v200, s[8:9]
	v_cndmask_b32_e64 v83, v83, v200, s[6:7]
	v_cndmask_b32_e32 v82, v82, v200, vcc
.LBB0_981:
	v_max3_f32 v68, v114, v82, v115
	v_max3_f32 v69, v83, v116, v84
	s_nop 10
	v_max_f32_e32 v70, v97, v97
	v_max3_f32 v68, v68, v117, v85
	v_max3_f32 v69, v69, v118, v86
	v_max_f32_e32 v71, v129, v129
	v_max3_f32 v68, v68, v119, v87
	v_max3_f32 v69, v69, v120, v88
	v_max_f32_e32 v70, v71, v70
	v_max3_f32 v68, v68, v121, v89
	v_max3_f32 v69, v69, v122, v90
	s_cmp_eq_u32 s87, 0
	v_max3_f32 v68, v68, v123, v91
	v_max3_f32 v69, v69, v124, v92
	s_cselect_b64 s[6:7], -1, 0
	v_max3_f32 v68, v68, v125, v93
	v_max3_f32 v69, v69, v126, v94
	s_cmp_lg_u32 s87, 0
	v_max3_f32 v68, v68, v127, v95
	v_max3_f32 v69, v69, v128, v96
	s_cselect_b64 s[76:77], -1, 0
	v_max3_f32 v68, v68, v69, v70
	s_and_b64 vcc, exec, s[6:7]
	v_mov_b32_e32 v69, v68
	s_nop 1
	v_permlane32_swap_b32_e32 v68, v69
	v_max_f32_e32 v69, v69, v69
	v_max_f32_e32 v68, v68, v68
	v_max_f32_e32 v68, v68, v69
	s_cbranch_vccnz .LBB0_986
	v_cmp_lt_f32_e32 vcc, s74, v68
	s_cbranch_vccz .LBB0_987
	v_max_f32_e32 v68, v68, v68
	v_max_f32_e32 v69, 0, v68
	v_exp_f32_e64 v68, -v69
	v_add_f32_e32 v205, v205, v69
	v_mul_f32_e32 v203, v203, v68
	v_pk_mul_f32 v[64:65], v[64:65], v[68:69] op_sel_hi:[1,0]
	v_pk_mul_f32 v[62:63], v[62:63], v[68:69] op_sel_hi:[1,0]
	v_pk_mul_f32 v[60:61], v[60:61], v[68:69] op_sel_hi:[1,0]
	v_pk_mul_f32 v[58:59], v[58:59], v[68:69] op_sel_hi:[1,0]
	v_pk_mul_f32 v[56:57], v[56:57], v[68:69] op_sel_hi:[1,0]
	v_pk_mul_f32 v[54:55], v[54:55], v[68:69] op_sel_hi:[1,0]
	v_pk_mul_f32 v[52:53], v[52:53], v[68:69] op_sel_hi:[1,0]
	v_pk_mul_f32 v[50:51], v[50:51], v[68:69] op_sel_hi:[1,0]
	v_pk_mul_f32 v[48:49], v[48:49], v[68:69] op_sel_hi:[1,0]
	v_pk_mul_f32 v[46:47], v[46:47], v[68:69] op_sel_hi:[1,0]
	v_pk_mul_f32 v[44:45], v[44:45], v[68:69] op_sel_hi:[1,0]
	v_pk_mul_f32 v[42:43], v[42:43], v[68:69] op_sel_hi:[1,0]
	v_pk_mul_f32 v[40:41], v[40:41], v[68:69] op_sel_hi:[1,0]
	v_pk_mul_f32 v[38:39], v[38:39], v[68:69] op_sel_hi:[1,0]
	v_pk_mul_f32 v[36:37], v[36:37], v[68:69] op_sel_hi:[1,0]
	v_pk_mul_f32 v[34:35], v[34:35], v[68:69] op_sel_hi:[1,0]
	v_sub_f32_e32 v114, v114, v69
	v_sub_f32_e32 v115, v115, v69
	v_sub_f32_e32 v116, v116, v69
	v_sub_f32_e32 v117, v117, v69
	v_sub_f32_e32 v118, v118, v69
	v_sub_f32_e32 v119, v119, v69
	v_sub_f32_e32 v120, v120, v69
	v_sub_f32_e32 v121, v121, v69
	v_sub_f32_e32 v122, v122, v69
	v_sub_f32_e32 v123, v123, v69
	v_sub_f32_e32 v124, v124, v69
	v_sub_f32_e32 v125, v125, v69
	v_sub_f32_e32 v126, v126, v69
	v_sub_f32_e32 v127, v127, v69
	v_sub_f32_e32 v128, v128, v69
	v_sub_f32_e32 v129, v129, v69
	v_sub_f32_e32 v82, v82, v69
	v_sub_f32_e32 v83, v83, v69
	v_sub_f32_e32 v84, v84, v69
	v_sub_f32_e32 v85, v85, v69
	v_sub_f32_e32 v86, v86, v69
	v_sub_f32_e32 v87, v87, v69
	v_sub_f32_e32 v88, v88, v69
	v_sub_f32_e32 v89, v89, v69
	v_sub_f32_e32 v90, v90, v69
	v_sub_f32_e32 v91, v91, v69
	v_sub_f32_e32 v92, v92, v69
	v_sub_f32_e32 v93, v93, v69
	v_sub_f32_e32 v94, v94, v69
	v_sub_f32_e32 v95, v95, v69
	v_sub_f32_e32 v96, v96, v69
	v_sub_f32_e32 v97, v97, v69
	v_sub_f32_e32 v230, v230, v69
	v_sub_f32_e32 v231, v231, v69
	v_sub_f32_e32 v232, v232, v69
	v_sub_f32_e32 v233, v233, v69
	v_sub_f32_e32 v234, v234, v69
	v_sub_f32_e32 v235, v235, v69
	v_sub_f32_e32 v236, v236, v69
	v_sub_f32_e32 v237, v237, v69
	v_sub_f32_e32 v238, v238, v69
	v_sub_f32_e32 v239, v239, v69
	v_sub_f32_e32 v240, v240, v69
	v_sub_f32_e32 v241, v241, v69
	v_sub_f32_e32 v242, v242, v69
	v_sub_f32_e32 v243, v243, v69
	v_sub_f32_e32 v244, v244, v69
	v_sub_f32_e32 v245, v245, v69
	s_branch .LBB0_987

.LBB0_986:
	v_mov_b32_e32 v205, v68
	v_sub_f32_e32 v114, v114, v68
	v_sub_f32_e32 v115, v115, v68
	v_sub_f32_e32 v116, v116, v68
	v_sub_f32_e32 v117, v117, v68
	v_sub_f32_e32 v118, v118, v68
	v_sub_f32_e32 v119, v119, v68
	v_sub_f32_e32 v120, v120, v68
	v_sub_f32_e32 v121, v121, v68
	v_sub_f32_e32 v122, v122, v68
	v_sub_f32_e32 v123, v123, v68
	v_sub_f32_e32 v124, v124, v68
	v_sub_f32_e32 v125, v125, v68
	v_sub_f32_e32 v126, v126, v68
	v_sub_f32_e32 v127, v127, v68
	v_sub_f32_e32 v128, v128, v68
	v_sub_f32_e32 v129, v129, v68
	v_sub_f32_e32 v82, v82, v68
	v_sub_f32_e32 v83, v83, v68
	v_sub_f32_e32 v84, v84, v68
	v_sub_f32_e32 v85, v85, v68
	v_sub_f32_e32 v86, v86, v68
	v_sub_f32_e32 v87, v87, v68
	v_sub_f32_e32 v88, v88, v68
	v_sub_f32_e32 v89, v89, v68
	v_sub_f32_e32 v90, v90, v68
	v_sub_f32_e32 v91, v91, v68
	v_sub_f32_e32 v92, v92, v68
	v_sub_f32_e32 v93, v93, v68
	v_sub_f32_e32 v94, v94, v68
	v_sub_f32_e32 v95, v95, v68
	v_sub_f32_e32 v96, v96, v68
	v_sub_f32_e32 v97, v97, v68
	v_sub_f32_e32 v230, 0, v68
	v_sub_f32_e32 v231, 0, v68
	v_sub_f32_e32 v232, 0, v68
	v_sub_f32_e32 v233, 0, v68
	v_sub_f32_e32 v234, 0, v68
	v_sub_f32_e32 v235, 0, v68
	v_sub_f32_e32 v236, 0, v68
	v_sub_f32_e32 v237, 0, v68
	v_sub_f32_e32 v238, 0, v68
	v_sub_f32_e32 v239, 0, v68
	v_sub_f32_e32 v240, 0, v68
	v_sub_f32_e32 v241, 0, v68
	v_sub_f32_e32 v242, 0, v68
	v_sub_f32_e32 v243, 0, v68
	v_sub_f32_e32 v244, 0, v68
	v_sub_f32_e32 v245, 0, v68
.LBB0_987:
	ds_read_b128 v[68:71], v66
	ds_read_b128 v[72:75], v66 offset:8192
	ds_read_b128 v[212:215], v67
	ds_read_b128 v[216:219], v67 offset:8192
	v_exp_f32_e32 v115, v115
	v_exp_f32_e32 v114, v114
	v_exp_f32_e32 v116, v116
	v_add_f32_e32 v66, 0, v114
	v_add_f32_e32 v66, v115, v66
	v_add_f32_e32 v66, v116, v66
	v_exp_f32_e32 v83, v83
	v_exp_f32_e32 v82, v82
	v_exp_f32_e32 v84, v84
	s_waitcnt lgkmcnt(3)
	v_mfma_f32_32x32x16_bf16 v[98:113], v[68:71], v[130:133], 0
	v_add_f32_e32 v66, v82, v66
	v_add_f32_e32 v66, v83, v66
	v_add_f32_e32 v211, v84, v66
	s_waitcnt lgkmcnt(2)
	v_mfma_f32_32x32x16_bf16 v[66:81], v[72:75], v[130:133], 0
	v_exp_f32_e32 v117, v117
	ds_read_b128 v[220:223], v210
	ds_read_b128 v[224:227], v210 offset:8192
	v_exp_f32_e32 v118, v118
	v_exp_f32_e32 v119, v119
	v_add_f32_e32 v210, v117, v211
	v_add_f32_e32 v210, v118, v210
	v_add_f32_e32 v210, v119, v210
	s_waitcnt lgkmcnt(3)
	v_mfma_f32_32x32x16_bf16 v[98:113], v[212:215], v[134:137], v[98:113]
	v_exp_f32_e32 v85, v85
	v_exp_f32_e32 v86, v86
	v_exp_f32_e32 v87, v87
	v_add_f32_e32 v210, v85, v210
	s_waitcnt lgkmcnt(2)
	v_mfma_f32_32x32x16_bf16 v[66:81], v[216:219], v[134:137], v[66:81]
	v_add_f32_e32 v210, v86, v210
	v_add_f32_e32 v228, v87, v210
	v_exp_f32_e32 v120, v120
	ds_read_b128 v[210:213], v209
	ds_read_b128 v[214:217], v209 offset:8192
	v_exp_f32_e32 v121, v121
	v_exp_f32_e32 v122, v122
	v_add_f32_e32 v209, v120, v228
	v_add_f32_e32 v209, v121, v209
	v_add_f32_e32 v209, v122, v209
	s_waitcnt lgkmcnt(3)
	v_mfma_f32_32x32x16_bf16 v[98:113], v[220:223], v[146:149], v[98:113]
	v_exp_f32_e32 v88, v88
	v_exp_f32_e32 v89, v89
	v_exp_f32_e32 v90, v90
	v_add_f32_e32 v209, v88, v209
	s_waitcnt lgkmcnt(2)
	v_mfma_f32_32x32x16_bf16 v[66:81], v[224:227], v[146:149], v[66:81]
	v_add_f32_e32 v209, v89, v209
	v_add_f32_e32 v209, v90, v209
	v_exp_f32_e32 v123, v123
	ds_read_b128 v[218:221], v208 offset:16384
	ds_read_b128 v[222:225], v208 offset:18432
	v_exp_f32_e32 v124, v124
	v_exp_f32_e32 v125, v125
	v_add_f32_e32 v208, v123, v209
	v_add_f32_e32 v208, v124, v208
	v_add_f32_e32 v208, v125, v208
	s_waitcnt lgkmcnt(3)
	v_mfma_f32_32x32x16_bf16 v[98:113], v[210:213], v[150:153], v[98:113]
	v_exp_f32_e32 v91, v91
	v_exp_f32_e32 v92, v92
	v_exp_f32_e32 v93, v93
	v_add_f32_e32 v208, v91, v208
	s_waitcnt lgkmcnt(2)
	v_mfma_f32_32x32x16_bf16 v[66:81], v[214:217], v[150:153], v[66:81]
	v_add_f32_e32 v208, v92, v208
	v_add_f32_e32 v226, v93, v208
	v_exp_f32_e32 v126, v126
	ds_read_b128 v[208:211], v207 offset:16384
	ds_read_b128 v[212:215], v207 offset:18432
	v_exp_f32_e32 v127, v127
	v_add_f32_e32 v207, v126, v226
	v_add_f32_e32 v207, v127, v207
	s_waitcnt lgkmcnt(3)
	v_mfma_f32_32x32x16_bf16 v[98:113], v[218:221], v[162:165], v[98:113]
	v_exp_f32_e32 v94, v94
	v_exp_f32_e32 v95, v95
	v_add_f32_e32 v207, v94, v207
	v_add_f32_e32 v207, v95, v207
	s_waitcnt lgkmcnt(2)
	v_mfma_f32_32x32x16_bf16 v[66:81], v[222:225], v[162:165], v[66:81]
	v_exp_f32_e32 v128, v128
	v_exp_f32_e32 v129, v129
	v_add_f32_e32 v207, v128, v207
	v_add_f32_e32 v207, v129, v207
	s_waitcnt lgkmcnt(1)
	v_mfma_f32_32x32x16_bf16 v[98:113], v[208:211], v[166:169], v[98:113]
	v_exp_f32_e32 v96, v96
	v_exp_f32_e32 v97, v97
	v_add_f32_e32 v207, v96, v207
	v_add_f32_e32 v207, v97, v207
	s_waitcnt lgkmcnt(0)
	v_mfma_f32_32x32x16_bf16 v[66:81], v[212:215], v[166:169], v[66:81]
	s_andn2_b64 vcc, exec, s[70:71]
	s_cbranch_vccnz .LBB0_989
	v_mov_b32_e32 v208, v1
	s_add_i32 s8, s84, s91
	v_ashrrev_i32_e32 v209, 3, v208
	v_and_b32_e32 v209, -4, v209
	v_and_or_b32 v208, v208, 31, s8
	v_sub_u32_e32 v208, v208, v209
	s_nop 0
	v_cmp_gt_i32_e64 s[68:69], 26, v208
	v_cmp_gt_i32_e64 s[70:71], 27, v208
	v_cmp_gt_i32_e64 s[66:67], 25, v208
	s_and_b64 s[68:69], s[70:71], s[68:69]
	v_cmp_gt_i32_e64 s[64:65], 24, v208
	s_and_b64 s[66:67], s[68:69], s[66:67]
	v_cmp_gt_i32_e64 s[62:63], 19, v208
	s_and_b64 s[64:65], s[66:67], s[64:65]
	v_cmp_gt_i32_e64 s[60:61], 18, v208
	s_and_b64 s[62:63], s[64:65], s[62:63]
	v_cmp_gt_i32_e64 s[58:59], 17, v208
	s_and_b64 s[60:61], s[62:63], s[60:61]
	v_cmp_gt_i32_e64 s[56:57], 16, v208
	s_and_b64 s[58:59], s[60:61], s[58:59]
	v_cmp_gt_i32_e64 s[54:55], 11, v208
	s_and_b64 s[56:57], s[58:59], s[56:57]
	v_cmp_gt_i32_e64 s[52:53], 10, v208
	s_and_b64 s[54:55], s[56:57], s[54:55]
	v_cmp_gt_i32_e64 s[50:51], 9, v208
	s_and_b64 s[52:53], s[54:55], s[52:53]
	v_cmp_gt_i32_e64 s[48:49], 8, v208
	s_and_b64 s[50:51], s[52:53], s[50:51]
	v_cmp_gt_i32_e64 s[46:47], 3, v208
	s_and_b64 s[48:49], s[50:51], s[48:49]
	v_cmp_gt_i32_e64 s[44:45], 2, v208
	s_and_b64 s[46:47], s[48:49], s[46:47]
	v_cmp_gt_i32_e64 s[42:43], 1, v208
	s_and_b64 s[44:45], s[46:47], s[44:45]
	v_cmp_gt_i32_e64 s[40:41], 0, v208
	s_and_b64 s[42:43], s[44:45], s[42:43]
	s_and_b64 s[40:41], s[42:43], s[40:41]
	v_cmp_gt_i32_e64 s[36:37], 58, v208
	v_cndmask_b32_e64 v98, v98, v200, s[40:41]
	v_cmp_gt_i32_e64 s[40:41], 59, v208
	v_cmp_gt_i32_e64 s[34:35], 57, v208
	s_and_b64 s[36:37], s[40:41], s[36:37]
	v_cmp_gt_i32_e64 s[30:31], 56, v208
	s_and_b64 s[34:35], s[36:37], s[34:35]
	v_cmp_gt_i32_e64 s[28:29], 51, v208
	s_and_b64 s[30:31], s[34:35], s[30:31]
	v_cmp_gt_i32_e64 s[26:27], 50, v208
	s_and_b64 s[28:29], s[30:31], s[28:29]
	v_cmp_gt_i32_e64 s[24:25], 49, v208
	s_and_b64 s[26:27], s[28:29], s[26:27]
	v_cmp_gt_i32_e64 s[22:23], 48, v208
	s_and_b64 s[24:25], s[26:27], s[24:25]
	v_cmp_gt_i32_e64 s[20:21], 43, v208
	s_and_b64 s[22:23], s[24:25], s[22:23]
	v_cmp_gt_i32_e64 s[18:19], 42, v208
	s_and_b64 s[20:21], s[22:23], s[20:21]
	v_cmp_gt_i32_e64 s[16:17], 41, v208
	s_and_b64 s[18:19], s[20:21], s[18:19]
	v_cmp_gt_i32_e64 s[14:15], 40, v208
	s_and_b64 s[16:17], s[18:19], s[16:17]
	v_cmp_gt_i32_e64 s[12:13], 35, v208
	s_and_b64 s[14:15], s[16:17], s[14:15]
	v_cmp_gt_i32_e64 s[10:11], 34, v208
	s_and_b64 s[12:13], s[14:15], s[12:13]
	v_cmp_gt_i32_e64 s[8:9], 33, v208
	s_and_b64 s[10:11], s[12:13], s[10:11]
	v_cmp_gt_i32_e32 vcc, 32, v208
	s_and_b64 s[8:9], s[10:11], s[8:9]
	s_and_b64 vcc, s[8:9], vcc
	v_cndmask_b32_e64 v113, v113, v200, s[70:71]
	v_cndmask_b32_e64 v112, v112, v200, s[68:69]
	v_cndmask_b32_e64 v111, v111, v200, s[66:67]
	v_cndmask_b32_e64 v110, v110, v200, s[64:65]
	v_cndmask_b32_e64 v109, v109, v200, s[62:63]
	v_cndmask_b32_e64 v108, v108, v200, s[60:61]
	v_cndmask_b32_e64 v107, v107, v200, s[58:59]
	v_cndmask_b32_e64 v106, v106, v200, s[56:57]
	v_cndmask_b32_e64 v105, v105, v200, s[54:55]
	v_cndmask_b32_e64 v104, v104, v200, s[52:53]
	v_cndmask_b32_e64 v103, v103, v200, s[50:51]
	v_cndmask_b32_e64 v102, v102, v200, s[48:49]
	v_cndmask_b32_e64 v101, v101, v200, s[46:47]
	v_cndmask_b32_e64 v100, v100, v200, s[44:45]
	v_cndmask_b32_e64 v99, v99, v200, s[42:43]
	v_cndmask_b32_e64 v81, v81, v200, s[40:41]
	v_cndmask_b32_e64 v80, v80, v200, s[36:37]
	v_cndmask_b32_e64 v79, v79, v200, s[34:35]
	v_cndmask_b32_e64 v78, v78, v200, s[30:31]
	v_cndmask_b32_e64 v77, v77, v200, s[28:29]
	v_cndmask_b32_e64 v76, v76, v200, s[26:27]
	v_cndmask_b32_e64 v75, v75, v200, s[24:25]
	v_cndmask_b32_e64 v74, v74, v200, s[22:23]
	v_cndmask_b32_e64 v73, v73, v200, s[20:21]
	v_cndmask_b32_e64 v72, v72, v200, s[18:19]
	v_cndmask_b32_e64 v71, v71, v200, s[16:17]
	v_cndmask_b32_e64 v70, v70, v200, s[14:15]
	v_cndmask_b32_e64 v69, v69, v200, s[12:13]
	v_cndmask_b32_e64 v68, v68, v200, s[10:11]
	v_cndmask_b32_e64 v67, v67, v200, s[8:9]
	v_cndmask_b32_e32 v66, v66, v200, vcc
